# v22: attention loop: P.V and K.Q fused into one 24-MFMA block, softmax VALU spread over 20 gaps, overflow test taken after the block (late rescale path), K.Q chains S0 then S1
# speedup vs baseline: 1.0562x; 1.0078x over previous
.Lat_stream:
	s_lshl_b32 s8, s7, 7
	s_mov_b32 s9, 0
	v_lshl_add_u64 v[182:183], v[166:167], 0, s[8:9]
	global_load_dwordx4 v[150:153], v[182:183], off
	global_load_dwordx4 v[146:149], v[182:183], off offset:32
	global_load_dwordx4 v[142:145], v[182:183], off offset:64
	global_load_dwordx4 v[138:141], v[182:183], off offset:96
	s_lshl_b64 s[14:15], s[46:47], 12
	s_add_u32 s14, s14, s74
	s_addc_u32 s15, s15, s75
	s_add_u32 s18, s14, 0x800
	s_addc_u32 s19, s15, 0
	s_add_i32 s8, s8, 0x400
	s_add_u32 s14, s14, s8
	s_addc_u32 s15, s15, 0
	s_mov_b32 s13, 0
	s_mov_b32 s17, 32768
	s_mov_b32 s85, 0
	s_add_i32 m0, s13, s68
	s_nop 0
	global_load_lds_dwordx4 v154, s[14:15]
	s_add_i32 m0, s17, s69
	s_nop 0
	global_load_lds_dwordx4 v155, s[18:19]
	s_add_i32 m0, m0, 0x400
	s_nop 0
	global_load_lds_dwordx4 v156, s[18:19]
	s_add_i32 s13, s13, 8192
	s_cmp_eq_u32 s13, 32768
	s_cselect_b32 s13, 0, s13
	s_add_i32 s17, s17, 16384
	s_cmp_eq_u32 s17, 114688
	s_cselect_b32 s17, 32768, s17
	s_add_i32 s85, s85, 1
	s_cmp_lt_u32 s85, s6
	s_cselect_b32 s8, 0x40000, 0
	s_add_u32 s14, s14, s8
	s_addc_u32 s15, s15, 0
	s_add_u32 s18, s18, s8
	s_addc_u32 s19, s19, 0
	s_add_i32 m0, s13, s68
	s_nop 0
	global_load_lds_dwordx4 v154, s[14:15]
	s_add_i32 m0, s17, s69
	s_nop 0
	global_load_lds_dwordx4 v155, s[18:19]
	s_add_i32 m0, m0, 0x400
	s_nop 0
	global_load_lds_dwordx4 v156, s[18:19]
	s_add_i32 s13, s13, 8192
	s_cmp_eq_u32 s13, 32768
	s_cselect_b32 s13, 0, s13
	s_add_i32 s17, s17, 16384
	s_cmp_eq_u32 s17, 114688
	s_cselect_b32 s17, 32768, s17
	s_add_i32 s85, s85, 1
	s_cmp_lt_u32 s85, s6
	s_cselect_b32 s8, 0x40000, 0
	s_add_u32 s14, s14, s8
	s_addc_u32 s15, s15, 0
	s_add_u32 s18, s18, s8
	s_addc_u32 s19, s19, 0
	s_add_i32 m0, s13, s68
	s_nop 0
	global_load_lds_dwordx4 v154, s[14:15]
	s_add_i32 m0, s17, s69
	s_nop 0
	global_load_lds_dwordx4 v155, s[18:19]
	s_add_i32 m0, m0, 0x400
	s_nop 0
	global_load_lds_dwordx4 v156, s[18:19]
	s_add_i32 s13, s13, 8192
	s_cmp_eq_u32 s13, 32768
	s_cselect_b32 s13, 0, s13
	s_add_i32 s17, s17, 16384
	s_cmp_eq_u32 s17, 114688
	s_cselect_b32 s17, 32768, s17
	s_add_i32 s85, s85, 1
	s_cmp_lt_u32 s85, s6
	s_cselect_b32 s8, 0x40000, 0
	s_add_u32 s14, s14, s8
	s_addc_u32 s15, s15, 0
	s_add_u32 s18, s18, s8
	s_addc_u32 s19, s19, 0
	v_mov_b32_e32 v0, 0
	v_mov_b32_e32 v1, v0
	v_mov_b32_e32 v2, v0
	v_mov_b32_e32 v3, v0
	v_mov_b32_e32 v4, v0
	v_mov_b32_e32 v5, v0
	v_mov_b32_e32 v6, v0
	v_mov_b32_e32 v7, v0
	v_mov_b32_e32 v8, v0
	v_mov_b32_e32 v9, v0
	v_mov_b32_e32 v10, v0
	v_mov_b32_e32 v11, v0
	v_mov_b32_e32 v12, v0
	v_mov_b32_e32 v13, v0
	v_mov_b32_e32 v14, v0
	v_mov_b32_e32 v15, v0
	v_mov_b32_e32 v16, v0
	v_mov_b32_e32 v17, v0
	v_mov_b32_e32 v18, v0
	v_mov_b32_e32 v19, v0
	v_mov_b32_e32 v20, v0
	v_mov_b32_e32 v21, v0
	v_mov_b32_e32 v22, v0
	v_mov_b32_e32 v23, v0
	v_mov_b32_e32 v24, v0
	v_mov_b32_e32 v25, v0
	v_mov_b32_e32 v26, v0
	v_mov_b32_e32 v27, v0
	v_mov_b32_e32 v28, v0
	v_mov_b32_e32 v29, v0
	v_mov_b32_e32 v30, v0
	v_mov_b32_e32 v31, v0
	v_mov_b32_e32 v32, v0
	v_mov_b32_e32 v33, v0
	v_mov_b32_e32 v34, v0
	v_mov_b32_e32 v35, v0
	v_mov_b32_e32 v36, v0
	v_mov_b32_e32 v37, v0
	v_mov_b32_e32 v38, v0
	v_mov_b32_e32 v39, v0
	v_mov_b32_e32 v40, v0
	v_mov_b32_e32 v41, v0
	v_mov_b32_e32 v42, v0
	v_mov_b32_e32 v43, v0
	v_mov_b32_e32 v44, v0
	v_mov_b32_e32 v45, v0
	v_mov_b32_e32 v46, v0
	v_mov_b32_e32 v47, v0
	v_mov_b32_e32 v48, v0
	v_mov_b32_e32 v49, v0
	v_mov_b32_e32 v50, v0
	v_mov_b32_e32 v51, v0
	v_mov_b32_e32 v52, v0
	v_mov_b32_e32 v53, v0
	v_mov_b32_e32 v54, v0
	v_mov_b32_e32 v55, v0
	v_mov_b32_e32 v56, v0
	v_mov_b32_e32 v57, v0
	v_mov_b32_e32 v58, v0
	v_mov_b32_e32 v59, v0
	v_mov_b32_e32 v60, v0
	v_mov_b32_e32 v61, v0
	v_mov_b32_e32 v62, v0
	v_mov_b32_e32 v63, v0
	v_mov_b32_e32 v64, v0
	v_mov_b32_e32 v65, v0
	v_mov_b32_e32 v66, v0
	v_mov_b32_e32 v67, v0
	v_mov_b32_e32 v68, v0
	v_mov_b32_e32 v69, v0
	v_mov_b32_e32 v70, v0
	v_mov_b32_e32 v71, v0
	v_mov_b32_e32 v72, v0
	v_mov_b32_e32 v73, v0
	v_mov_b32_e32 v74, v0
	v_mov_b32_e32 v75, v0
	v_mov_b32_e32 v76, v0
	v_mov_b32_e32 v77, v0
	v_mov_b32_e32 v78, v0
	v_mov_b32_e32 v79, v0
	v_mov_b32_e32 v80, 0
	v_mov_b32_e32 v81, 0
	s_mov_b32 s5, 0
	s_waitcnt vmcnt(3)
	s_barrier
	s_add_i32 m0, s13, s68
	s_nop 0
	global_load_lds_dwordx4 v154, s[14:15]
	s_add_i32 m0, s17, s69
	s_nop 0
	global_load_lds_dwordx4 v155, s[18:19]
	s_add_i32 m0, m0, 0x400
	s_nop 0
	global_load_lds_dwordx4 v156, s[18:19]
	s_add_i32 s13, s13, 8192
	s_cmp_eq_u32 s13, 32768
	s_cselect_b32 s13, 0, s13
	s_add_i32 s17, s17, 16384
	s_cmp_eq_u32 s17, 114688
	s_cselect_b32 s17, 32768, s17
	s_add_i32 s85, s85, 1
	s_cmp_lt_u32 s85, s6
	s_cselect_b32 s8, 0x40000, 0
	s_add_u32 s14, s14, s8
	s_addc_u32 s15, s15, 0
	s_add_u32 s18, s18, s8
	s_addc_u32 s19, s19, 0
	s_mov_b32 s12, 0
	v_add_u32_e32 v188, s12, v157
	v_add_u32_e32 v189, s12, v158
	v_add_u32_e32 v222, s12, v159
	v_add_u32_e32 v223, s12, v160
	ds_read_b128 v[224:227], v188
	ds_read_b128 v[228:231], v189
	ds_read_b128 v[232:235], v222
	ds_read_b128 v[236:239], v223
	ds_read_b128 v[240:243], v188 offset:4096
	ds_read_b128 v[130:133], v189 offset:4096
	ds_read_b128 v[134:137], v222 offset:4096
	ds_read_b128 v[184:187], v223 offset:4096
	s_waitcnt lgkmcnt(7)
	v_mfma_f32_32x32x16_bf16 v[82:97], v[224:227], v[150:153], v[64:79]
	s_waitcnt lgkmcnt(6)
	v_mfma_f32_32x32x16_bf16 v[82:97], v[228:231], v[146:149], v[82:97]
	s_waitcnt lgkmcnt(5)
	v_mfma_f32_32x32x16_bf16 v[82:97], v[232:235], v[142:145], v[82:97]
	s_waitcnt lgkmcnt(4)
	v_mfma_f32_32x32x16_bf16 v[82:97], v[236:239], v[138:141], v[82:97]
	s_waitcnt lgkmcnt(3)
	v_mfma_f32_32x32x16_bf16 v[98:113], v[240:243], v[150:153], v[64:79]
	s_waitcnt lgkmcnt(2)
	v_mfma_f32_32x32x16_bf16 v[98:113], v[130:133], v[146:149], v[98:113]
	s_waitcnt lgkmcnt(1)
	v_mfma_f32_32x32x16_bf16 v[98:113], v[134:137], v[142:145], v[98:113]
	s_waitcnt lgkmcnt(0)
	v_mfma_f32_32x32x16_bf16 v[98:113], v[184:187], v[138:141], v[98:113]
	s_nop 11
	v_max_f32_e32 v181, v82, v98
	v_max3_f32 v181, v181, v83, v99
	v_max3_f32 v181, v181, v84, v100
	v_max3_f32 v181, v181, v85, v101
	v_max3_f32 v181, v181, v86, v102
	v_max3_f32 v181, v181, v87, v103
	v_max3_f32 v181, v181, v88, v104
	v_max3_f32 v181, v181, v89, v105
	v_max3_f32 v181, v181, v90, v106
	v_max3_f32 v181, v181, v91, v107
	v_max3_f32 v181, v181, v92, v108
	v_max3_f32 v181, v181, v93, v109
	v_max3_f32 v181, v181, v94, v110
	v_max3_f32 v181, v181, v95, v111
	v_max3_f32 v181, v181, v96, v112
	v_max3_f32 v181, v181, v97, v113
	ds_bpermute_b32 v182, v214, v181
	s_waitcnt lgkmcnt(0)
	v_max_f32_e32 v80, v181, v182
	v_xor_b32_e32 v64, 0x80000000, v80
	v_mov_b32_e32 v65, v64
	v_mov_b32_e32 v66, v64
	v_mov_b32_e32 v67, v64
	v_mov_b32_e32 v68, v64
	v_mov_b32_e32 v69, v64
	v_mov_b32_e32 v70, v64
	v_mov_b32_e32 v71, v64
	v_mov_b32_e32 v72, v64
	v_mov_b32_e32 v73, v64
	v_mov_b32_e32 v74, v64
	v_mov_b32_e32 v75, v64
	v_mov_b32_e32 v76, v64
	v_mov_b32_e32 v77, v64
	v_mov_b32_e32 v78, v64
	v_mov_b32_e32 v79, v64
	v_sub_f32_e32 v82, v82, v80
	v_sub_f32_e32 v83, v83, v80
	v_sub_f32_e32 v84, v84, v80
	v_sub_f32_e32 v85, v85, v80
	v_sub_f32_e32 v86, v86, v80
	v_sub_f32_e32 v87, v87, v80
	v_sub_f32_e32 v88, v88, v80
	v_sub_f32_e32 v89, v89, v80
	v_sub_f32_e32 v90, v90, v80
	v_sub_f32_e32 v91, v91, v80
	v_sub_f32_e32 v92, v92, v80
	v_sub_f32_e32 v93, v93, v80
	v_sub_f32_e32 v94, v94, v80
	v_sub_f32_e32 v95, v95, v80
	v_sub_f32_e32 v96, v96, v80
	v_sub_f32_e32 v97, v97, v80
	v_sub_f32_e32 v98, v98, v80
	v_sub_f32_e32 v99, v99, v80
	v_sub_f32_e32 v100, v100, v80
	v_sub_f32_e32 v101, v101, v80
	v_sub_f32_e32 v102, v102, v80
	v_sub_f32_e32 v103, v103, v80
	v_sub_f32_e32 v104, v104, v80
	v_sub_f32_e32 v105, v105, v80
	v_sub_f32_e32 v106, v106, v80
	v_sub_f32_e32 v107, v107, v80
	v_sub_f32_e32 v108, v108, v80
	v_sub_f32_e32 v109, v109, v80
	v_sub_f32_e32 v110, v110, v80
	v_sub_f32_e32 v111, v111, v80
	v_sub_f32_e32 v112, v112, v80
	v_sub_f32_e32 v113, v113, v80
	v_mov_b32_e32 v180, 0
	v_exp_f32_e32 v82, v82
	v_exp_f32_e32 v83, v83
	v_add_f32_e32 v180, v180, v82
	v_exp_f32_e32 v84, v84
	v_add_f32_e32 v180, v180, v83
	v_exp_f32_e32 v85, v85
	v_add_f32_e32 v180, v180, v84
	v_exp_f32_e32 v86, v86
	v_add_f32_e32 v180, v180, v85
	v_exp_f32_e32 v87, v87
	v_add_f32_e32 v180, v180, v86
	v_exp_f32_e32 v88, v88
	v_add_f32_e32 v180, v180, v87
	v_exp_f32_e32 v89, v89
	v_add_f32_e32 v180, v180, v88
	v_exp_f32_e32 v90, v90
	v_add_f32_e32 v180, v180, v89
	v_exp_f32_e32 v91, v91
	v_add_f32_e32 v180, v180, v90
	v_exp_f32_e32 v92, v92
	v_add_f32_e32 v180, v180, v91
	v_exp_f32_e32 v93, v93
	v_add_f32_e32 v180, v180, v92
	v_exp_f32_e32 v94, v94
	v_add_f32_e32 v180, v180, v93
	v_exp_f32_e32 v95, v95
	v_add_f32_e32 v180, v180, v94
	v_exp_f32_e32 v96, v96
	v_add_f32_e32 v180, v180, v95
	v_exp_f32_e32 v97, v97
	v_add_f32_e32 v180, v180, v96
	v_exp_f32_e32 v98, v98
	v_add_f32_e32 v180, v180, v97
	v_exp_f32_e32 v99, v99
	v_add_f32_e32 v180, v180, v98
	v_exp_f32_e32 v100, v100
	v_add_f32_e32 v180, v180, v99
	v_exp_f32_e32 v101, v101
	v_add_f32_e32 v180, v180, v100
	v_exp_f32_e32 v102, v102
	v_add_f32_e32 v180, v180, v101
	v_exp_f32_e32 v103, v103
	v_add_f32_e32 v180, v180, v102
	v_exp_f32_e32 v104, v104
	v_add_f32_e32 v180, v180, v103
	v_exp_f32_e32 v105, v105
	v_add_f32_e32 v180, v180, v104
	v_exp_f32_e32 v106, v106
	v_add_f32_e32 v180, v180, v105
	v_exp_f32_e32 v107, v107
	v_add_f32_e32 v180, v180, v106
	v_exp_f32_e32 v108, v108
	v_add_f32_e32 v180, v180, v107
	v_exp_f32_e32 v109, v109
	v_add_f32_e32 v180, v180, v108
	v_exp_f32_e32 v110, v110
	v_add_f32_e32 v180, v180, v109
	v_exp_f32_e32 v111, v111
	v_add_f32_e32 v180, v180, v110
	v_exp_f32_e32 v112, v112
	v_add_f32_e32 v180, v180, v111
	v_exp_f32_e32 v113, v113
	v_add_f32_e32 v180, v180, v112
	s_nop 0
	v_add_f32_e32 v180, v180, v113
	v_cvt_pk_bf16_f32 v114, v82, v83
	v_cvt_pk_bf16_f32 v115, v84, v85
	v_cvt_pk_bf16_f32 v116, v86, v87
	v_cvt_pk_bf16_f32 v117, v88, v89
	v_cvt_pk_bf16_f32 v118, v90, v91
	v_cvt_pk_bf16_f32 v119, v92, v93
	v_cvt_pk_bf16_f32 v120, v94, v95
	v_cvt_pk_bf16_f32 v121, v96, v97
	v_cvt_pk_bf16_f32 v122, v98, v99
	v_cvt_pk_bf16_f32 v123, v100, v101
	v_cvt_pk_bf16_f32 v124, v102, v103
	v_cvt_pk_bf16_f32 v125, v104, v105
	v_cvt_pk_bf16_f32 v126, v106, v107
	v_cvt_pk_bf16_f32 v127, v108, v109
	v_cvt_pk_bf16_f32 v128, v110, v111
	v_cvt_pk_bf16_f32 v129, v112, v113
	v_cmp_ngt_f32_e32 vcc, s23, v180
	s_cbranch_vccz .Lat_norescale_1
	ds_bpermute_b32 v182, v214, v180
	s_waitcnt lgkmcnt(0)
	v_add_f32_e32 v182, v180, v182
	v_min_f32_e32 v182, 0x7f61b1e6, v182
	v_log_f32_e32 v182, v182
	s_nop 0
	v_floor_f32_e32 v182, v182
	v_max_f32_e32 v182, 0, v182
	v_exp_f32_e64 v183, -v182
	v_add_f32_e32 v80, v80, v182
	v_mul_f32_e32 v81, v81, v183
	v_mul_f32_e32 v180, v180, v183
	v_xor_b32_e32 v64, 0x80000000, v80
	v_mov_b32_e32 v65, v64
	v_mov_b32_e32 v66, v64
	v_mov_b32_e32 v67, v64
	v_mov_b32_e32 v68, v64
	v_mov_b32_e32 v69, v64
	v_mov_b32_e32 v70, v64
	v_mov_b32_e32 v71, v64
	v_mov_b32_e32 v72, v64
	v_mov_b32_e32 v73, v64
	v_mov_b32_e32 v74, v64
	v_mov_b32_e32 v75, v64
	v_mov_b32_e32 v76, v64
	v_mov_b32_e32 v77, v64
	v_mov_b32_e32 v78, v64
	v_mov_b32_e32 v79, v64
	v_mul_f32_e32 v82, v82, v183
	v_mul_f32_e32 v83, v83, v183
	v_mul_f32_e32 v84, v84, v183
	v_mul_f32_e32 v85, v85, v183
	v_mul_f32_e32 v86, v86, v183
	v_mul_f32_e32 v87, v87, v183
	v_mul_f32_e32 v88, v88, v183
	v_mul_f32_e32 v89, v89, v183
	v_mul_f32_e32 v90, v90, v183
	v_mul_f32_e32 v91, v91, v183
	v_mul_f32_e32 v92, v92, v183
	v_mul_f32_e32 v93, v93, v183
	v_mul_f32_e32 v94, v94, v183
	v_mul_f32_e32 v95, v95, v183
	v_mul_f32_e32 v96, v96, v183
	v_mul_f32_e32 v97, v97, v183
	v_mul_f32_e32 v98, v98, v183
	v_mul_f32_e32 v99, v99, v183
	v_mul_f32_e32 v100, v100, v183
	v_mul_f32_e32 v101, v101, v183
	v_mul_f32_e32 v102, v102, v183
	v_mul_f32_e32 v103, v103, v183
	v_mul_f32_e32 v104, v104, v183
	v_mul_f32_e32 v105, v105, v183
	v_mul_f32_e32 v106, v106, v183
	v_mul_f32_e32 v107, v107, v183
	v_mul_f32_e32 v108, v108, v183
	v_mul_f32_e32 v109, v109, v183
	v_mul_f32_e32 v110, v110, v183
	v_mul_f32_e32 v111, v111, v183
	v_mul_f32_e32 v112, v112, v183
	v_mul_f32_e32 v113, v113, v183
	v_mul_f32_e32 v0, v0, v183
	v_mul_f32_e32 v1, v1, v183
	v_mul_f32_e32 v2, v2, v183
	v_mul_f32_e32 v3, v3, v183
	v_mul_f32_e32 v4, v4, v183
	v_mul_f32_e32 v5, v5, v183
	v_mul_f32_e32 v6, v6, v183
	v_mul_f32_e32 v7, v7, v183
	v_mul_f32_e32 v8, v8, v183
	v_mul_f32_e32 v9, v9, v183
	v_mul_f32_e32 v10, v10, v183
	v_mul_f32_e32 v11, v11, v183
	v_mul_f32_e32 v12, v12, v183
	v_mul_f32_e32 v13, v13, v183
	v_mul_f32_e32 v14, v14, v183
	v_mul_f32_e32 v15, v15, v183
	v_mul_f32_e32 v16, v16, v183
	v_mul_f32_e32 v17, v17, v183
	v_mul_f32_e32 v18, v18, v183
	v_mul_f32_e32 v19, v19, v183
	v_mul_f32_e32 v20, v20, v183
	v_mul_f32_e32 v21, v21, v183
	v_mul_f32_e32 v22, v22, v183
	v_mul_f32_e32 v23, v23, v183
	v_mul_f32_e32 v24, v24, v183
	v_mul_f32_e32 v25, v25, v183
	v_mul_f32_e32 v26, v26, v183
	v_mul_f32_e32 v27, v27, v183
	v_mul_f32_e32 v28, v28, v183
	v_mul_f32_e32 v29, v29, v183
	v_mul_f32_e32 v30, v30, v183
	v_mul_f32_e32 v31, v31, v183
	v_mul_f32_e32 v32, v32, v183
	v_mul_f32_e32 v33, v33, v183
	v_mul_f32_e32 v34, v34, v183
	v_mul_f32_e32 v35, v35, v183
	v_mul_f32_e32 v36, v36, v183
	v_mul_f32_e32 v37, v37, v183
	v_mul_f32_e32 v38, v38, v183
	v_mul_f32_e32 v39, v39, v183
	v_mul_f32_e32 v40, v40, v183
	v_mul_f32_e32 v41, v41, v183
	v_mul_f32_e32 v42, v42, v183
	v_mul_f32_e32 v43, v43, v183
	v_mul_f32_e32 v44, v44, v183
	v_mul_f32_e32 v45, v45, v183
	v_mul_f32_e32 v46, v46, v183
	v_mul_f32_e32 v47, v47, v183
	v_mul_f32_e32 v48, v48, v183
	v_mul_f32_e32 v49, v49, v183
	v_mul_f32_e32 v50, v50, v183
	v_mul_f32_e32 v51, v51, v183
	v_mul_f32_e32 v52, v52, v183
	v_mul_f32_e32 v53, v53, v183
	v_mul_f32_e32 v54, v54, v183
	v_mul_f32_e32 v55, v55, v183
	v_mul_f32_e32 v56, v56, v183
	v_mul_f32_e32 v57, v57, v183
	v_mul_f32_e32 v58, v58, v183
	v_mul_f32_e32 v59, v59, v183
	v_mul_f32_e32 v60, v60, v183
	v_mul_f32_e32 v61, v61, v183
	v_mul_f32_e32 v62, v62, v183
	v_mul_f32_e32 v63, v63, v183
	v_cvt_pk_bf16_f32 v114, v82, v83
	v_cvt_pk_bf16_f32 v115, v84, v85
	v_cvt_pk_bf16_f32 v116, v86, v87
	v_cvt_pk_bf16_f32 v117, v88, v89
	v_cvt_pk_bf16_f32 v118, v90, v91
	v_cvt_pk_bf16_f32 v119, v92, v93
	v_cvt_pk_bf16_f32 v120, v94, v95
	v_cvt_pk_bf16_f32 v121, v96, v97
	v_cvt_pk_bf16_f32 v122, v98, v99
	v_cvt_pk_bf16_f32 v123, v100, v101
	v_cvt_pk_bf16_f32 v124, v102, v103
	v_cvt_pk_bf16_f32 v125, v104, v105
	v_cvt_pk_bf16_f32 v126, v106, v107
	v_cvt_pk_bf16_f32 v127, v108, v109
	v_cvt_pk_bf16_f32 v128, v110, v111
	v_cvt_pk_bf16_f32 v129, v112, v113
.Lat_norescale_1:
	v_add_f32_e32 v81, v81, v180
	s_cmp_lt_i32 s81, 1
	s_cbranch_scc1 .Lat_noqk1_2
	s_mov_b32 s12, 8192
	v_add_u32_e32 v188, s12, v157
	v_add_u32_e32 v189, s12, v158
	v_add_u32_e32 v222, s12, v159
	v_add_u32_e32 v223, s12, v160
	ds_read_b128 v[224:227], v188
	ds_read_b128 v[228:231], v189
	ds_read_b128 v[232:235], v222
	ds_read_b128 v[236:239], v223
	ds_read_b128 v[240:243], v188 offset:4096
	ds_read_b128 v[130:133], v189 offset:4096
	ds_read_b128 v[134:137], v222 offset:4096
	ds_read_b128 v[184:187], v223 offset:4096
	s_waitcnt lgkmcnt(7)
	v_mfma_f32_32x32x16_bf16 v[82:97], v[224:227], v[150:153], v[64:79]
	s_waitcnt lgkmcnt(6)
	v_mfma_f32_32x32x16_bf16 v[82:97], v[228:231], v[146:149], v[82:97]
	s_waitcnt lgkmcnt(5)
	v_mfma_f32_32x32x16_bf16 v[82:97], v[232:235], v[142:145], v[82:97]
	s_waitcnt lgkmcnt(4)
	v_mfma_f32_32x32x16_bf16 v[82:97], v[236:239], v[138:141], v[82:97]
	s_waitcnt lgkmcnt(3)
	v_mfma_f32_32x32x16_bf16 v[98:113], v[240:243], v[150:153], v[64:79]
	s_waitcnt lgkmcnt(2)
	v_mfma_f32_32x32x16_bf16 v[98:113], v[130:133], v[146:149], v[98:113]
	s_waitcnt lgkmcnt(1)
	v_mfma_f32_32x32x16_bf16 v[98:113], v[134:137], v[142:145], v[98:113]
	s_waitcnt lgkmcnt(0)
	v_mfma_f32_32x32x16_bf16 v[98:113], v[184:187], v[138:141], v[98:113]

.Lat_loop:
	s_add_i32 s16, s81, 1
	s_cmp_gt_i32 s5, s16
	s_cbranch_scc1 .Lat_noqk_3
	v_add_u32_e32 v188, s12, v157
	v_add_u32_e32 v189, s12, v158
	v_add_u32_e32 v222, s12, v159
	v_add_u32_e32 v223, s12, v160
	s_cmp_gt_i32 s5, s81
	s_cbranch_scc1 .Lat_pvonly_6
	s_cmp_ge_i32 s5, s81
	s_cbranch_scc1 .Lat_xlast_7
	s_waitcnt lgkmcnt(14)
	v_mfma_f32_32x32x16_bf16 v[0:15], v[224:227], v[114:117], v[0:15]
	v_exp_f32_e32 v82, v82
	v_exp_f32_e32 v83, v83
	ds_read_b64_tr_b16 v[224:225], v215 offset:8192
	ds_read_b64_tr_b16 v[226:227], v215 offset:10240
	s_waitcnt lgkmcnt(14)
	v_mfma_f32_32x32x16_bf16 v[16:31], v[228:231], v[114:117], v[16:31]
	v_exp_f32_e32 v84, v84
	v_exp_f32_e32 v85, v85
	v_add_f32_e32 v180, v82, v83
	ds_read_b64_tr_b16 v[228:229], v165 offset:8192
	ds_read_b64_tr_b16 v[230:231], v165 offset:10240
	s_waitcnt lgkmcnt(14)
	v_mfma_f32_32x32x16_bf16 v[32:47], v[232:235], v[114:117], v[32:47]
	v_exp_f32_e32 v86, v86
	v_exp_f32_e32 v87, v87
	v_add_f32_e32 v180, v180, v84
	v_add_f32_e32 v180, v180, v85
	ds_read_b64_tr_b16 v[232:233], v216 offset:8192
	ds_read_b64_tr_b16 v[234:235], v216 offset:10240
	s_waitcnt lgkmcnt(14)
	v_mfma_f32_32x32x16_bf16 v[48:63], v[236:239], v[114:117], v[48:63]
	v_exp_f32_e32 v88, v88
	v_exp_f32_e32 v89, v89
	v_add_f32_e32 v180, v180, v86
	v_add_f32_e32 v180, v180, v87
	ds_read_b64_tr_b16 v[236:237], v217 offset:8192
	ds_read_b64_tr_b16 v[238:239], v217 offset:10240
	s_waitcnt lgkmcnt(14)
	v_mfma_f32_32x32x16_bf16 v[0:15], v[240:243], v[118:121], v[0:15]
	v_exp_f32_e32 v90, v90
	v_exp_f32_e32 v91, v91
	v_add_f32_e32 v180, v180, v88
	v_cvt_pk_bf16_f32 v114, v82, v83
	ds_read_b64_tr_b16 v[240:241], v215 offset:12288
	ds_read_b64_tr_b16 v[242:243], v215 offset:14336
	s_waitcnt lgkmcnt(14)
	v_mfma_f32_32x32x16_bf16 v[16:31], v[130:133], v[118:121], v[16:31]
	v_exp_f32_e32 v92, v92
	v_exp_f32_e32 v93, v93
	v_add_f32_e32 v180, v180, v89
	v_cvt_pk_bf16_f32 v115, v84, v85
	ds_read_b64_tr_b16 v[130:131], v165 offset:12288
	ds_read_b64_tr_b16 v[132:133], v165 offset:14336
	s_waitcnt lgkmcnt(14)
	v_mfma_f32_32x32x16_bf16 v[32:47], v[134:137], v[118:121], v[32:47]
	v_exp_f32_e32 v94, v94
	v_exp_f32_e32 v95, v95
	v_add_f32_e32 v180, v180, v90
	v_cvt_pk_bf16_f32 v116, v86, v87
	ds_read_b64_tr_b16 v[134:135], v216 offset:12288
	ds_read_b64_tr_b16 v[136:137], v216 offset:14336
	s_waitcnt lgkmcnt(14)
	v_mfma_f32_32x32x16_bf16 v[48:63], v[184:187], v[118:121], v[48:63]
	v_exp_f32_e32 v96, v96
	v_exp_f32_e32 v97, v97
	v_add_f32_e32 v180, v180, v91
	v_cvt_pk_bf16_f32 v117, v88, v89
	ds_read_b64_tr_b16 v[184:185], v217 offset:12288
	ds_read_b64_tr_b16 v[186:187], v217 offset:14336
	s_waitcnt lgkmcnt(14)
	v_mfma_f32_32x32x16_bf16 v[0:15], v[224:227], v[122:125], v[0:15]
	v_exp_f32_e32 v98, v98
	v_exp_f32_e32 v99, v99
	v_add_f32_e32 v180, v180, v92
	v_cvt_pk_bf16_f32 v118, v90, v91
	s_waitcnt lgkmcnt(12)
	v_mfma_f32_32x32x16_bf16 v[16:31], v[228:231], v[122:125], v[16:31]
	v_exp_f32_e32 v100, v100
	v_exp_f32_e32 v101, v101
	v_add_f32_e32 v180, v180, v93
	v_cvt_pk_bf16_f32 v119, v92, v93
	s_waitcnt lgkmcnt(10)
	v_mfma_f32_32x32x16_bf16 v[32:47], v[232:235], v[122:125], v[32:47]
	v_exp_f32_e32 v102, v102
	v_exp_f32_e32 v103, v103
	v_add_f32_e32 v180, v180, v94
	v_cvt_pk_bf16_f32 v120, v94, v95
	s_waitcnt lgkmcnt(8)
	v_mfma_f32_32x32x16_bf16 v[48:63], v[236:239], v[122:125], v[48:63]
	v_exp_f32_e32 v104, v104
	v_exp_f32_e32 v105, v105
	v_add_f32_e32 v180, v180, v95
	v_cvt_pk_bf16_f32 v121, v96, v97
	ds_read_b128 v[224:227], v188
	ds_read_b128 v[228:231], v189
	ds_read_b128 v[232:235], v222
	ds_read_b128 v[236:239], v223
	s_waitcnt lgkmcnt(10)
	v_mfma_f32_32x32x16_bf16 v[0:15], v[240:243], v[126:129], v[0:15]
	v_exp_f32_e32 v106, v106
	v_exp_f32_e32 v107, v107
	v_add_f32_e32 v180, v180, v96
	v_add_f32_e32 v180, v180, v97
	s_waitcnt lgkmcnt(8)
	v_mfma_f32_32x32x16_bf16 v[16:31], v[130:133], v[126:129], v[16:31]
	v_exp_f32_e32 v108, v108
	v_exp_f32_e32 v109, v109
	v_add_f32_e32 v180, v180, v98
	v_add_f32_e32 v180, v180, v99
	s_waitcnt lgkmcnt(6)
	v_mfma_f32_32x32x16_bf16 v[32:47], v[134:137], v[126:129], v[32:47]
	v_exp_f32_e32 v110, v110
	v_exp_f32_e32 v111, v111
	v_add_f32_e32 v180, v180, v100
	v_add_f32_e32 v180, v180, v101
	s_waitcnt lgkmcnt(4)
	v_mfma_f32_32x32x16_bf16 v[48:63], v[184:187], v[126:129], v[48:63]
	v_exp_f32_e32 v112, v112
	v_exp_f32_e32 v113, v113
	v_add_f32_e32 v180, v180, v102
	v_add_f32_e32 v180, v180, v103
	ds_read_b128 v[240:243], v188 offset:4096
	ds_read_b128 v[130:133], v189 offset:4096
	ds_read_b128 v[134:137], v222 offset:4096
	ds_read_b128 v[184:187], v223 offset:4096
	s_waitcnt lgkmcnt(7)
	v_mfma_f32_32x32x16_bf16 v[82:97], v[224:227], v[150:153], v[64:79]
	v_add_f32_e32 v180, v180, v104
	v_add_f32_e32 v180, v180, v105
	v_add_f32_e32 v180, v180, v106
	v_cvt_pk_bf16_f32 v122, v98, v99
	v_cvt_pk_bf16_f32 v123, v100, v101
	s_add_i32 m0, s13, s68
	s_nop 0
	global_load_lds_dwordx4 v154, s[14:15]
	s_waitcnt lgkmcnt(6)
	v_mfma_f32_32x32x16_bf16 v[82:97], v[228:231], v[146:149], v[82:97]
	v_add_f32_e32 v180, v180, v107
	v_add_f32_e32 v180, v180, v108
	v_add_f32_e32 v180, v180, v109
	v_cvt_pk_bf16_f32 v124, v102, v103
	v_cvt_pk_bf16_f32 v125, v104, v105
	s_add_i32 m0, s17, s69
	s_nop 0
	global_load_lds_dwordx4 v155, s[18:19]
	s_waitcnt lgkmcnt(5)
	v_mfma_f32_32x32x16_bf16 v[82:97], v[232:235], v[142:145], v[82:97]
	v_add_f32_e32 v180, v180, v110
	v_add_f32_e32 v180, v180, v111
	v_cvt_pk_bf16_f32 v126, v106, v107
	v_cvt_pk_bf16_f32 v127, v108, v109
	s_add_i32 m0, m0, 0x400
	s_nop 0
	global_load_lds_dwordx4 v156, s[18:19]
	s_waitcnt lgkmcnt(4)
	v_mfma_f32_32x32x16_bf16 v[82:97], v[236:239], v[138:141], v[82:97]
	v_add_f32_e32 v180, v180, v112
	v_add_f32_e32 v180, v180, v113
	v_cvt_pk_bf16_f32 v128, v110, v111
	v_cvt_pk_bf16_f32 v129, v112, v113
	v_cmp_ngt_f32_e32 vcc, s23, v180
	s_add_i32 s13, s13, 8192
	s_cmp_eq_u32 s13, 32768
	s_cselect_b32 s13, 0, s13
	s_add_i32 s17, s17, 16384
	s_cmp_eq_u32 s17, 114688
	s_cselect_b32 s17, 32768, s17
	s_add_i32 s85, s85, 1
	s_cmp_lt_u32 s85, s6
	s_cselect_b32 s8, 0x40000, 0
	s_add_u32 s14, s14, s8
	s_addc_u32 s15, s15, 0
	s_add_u32 s18, s18, s8
	s_addc_u32 s19, s19, 0
	s_add_i32 s5, s5, 1
	s_add_i32 s12, s12, 8192
	s_cmp_eq_u32 s12, 32768
	s_cselect_b32 s12, 0, s12
	s_add_i32 s84, s84, 16384
	s_cmp_eq_u32 s84, 114688
	s_cselect_b32 s84, 32768, s84
	s_waitcnt lgkmcnt(3)
	v_mfma_f32_32x32x16_bf16 v[98:113], v[240:243], v[150:153], v[64:79]
	v_add_u32_e32 v215, s84, v161
	v_add_u32_e32 v165, s84, v162
	v_add_u32_e32 v216, s84, v163
	v_add_u32_e32 v217, s84, v164
	ds_read_b64_tr_b16 v[224:225], v215 offset:0
	ds_read_b64_tr_b16 v[226:227], v215 offset:2048
	s_waitcnt lgkmcnt(4)
	v_mfma_f32_32x32x16_bf16 v[98:113], v[130:133], v[146:149], v[98:113]
	ds_read_b64_tr_b16 v[228:229], v165 offset:0
	ds_read_b64_tr_b16 v[230:231], v165 offset:2048
	ds_read_b64_tr_b16 v[232:233], v216 offset:0
	ds_read_b64_tr_b16 v[234:235], v216 offset:2048
	s_waitcnt lgkmcnt(7)
	v_mfma_f32_32x32x16_bf16 v[98:113], v[134:137], v[142:145], v[98:113]
	ds_read_b64_tr_b16 v[236:237], v217 offset:0
	ds_read_b64_tr_b16 v[238:239], v217 offset:2048
	s_waitcnt lgkmcnt(8)
	v_mfma_f32_32x32x16_bf16 v[98:113], v[184:187], v[138:141], v[98:113]
	ds_read_b64_tr_b16 v[240:241], v215 offset:4096
	ds_read_b64_tr_b16 v[242:243], v215 offset:6144
	ds_read_b64_tr_b16 v[130:131], v165 offset:4096
	ds_read_b64_tr_b16 v[132:133], v165 offset:6144
	ds_read_b64_tr_b16 v[134:135], v216 offset:4096
	ds_read_b64_tr_b16 v[136:137], v216 offset:6144
	ds_read_b64_tr_b16 v[184:185], v217 offset:4096
	ds_read_b64_tr_b16 v[186:187], v217 offset:6144
	s_cbranch_vccz .Lat_norescale_8
	ds_bpermute_b32 v182, v214, v180
	s_waitcnt lgkmcnt(0)
	v_add_f32_e32 v182, v180, v182
	v_min_f32_e32 v182, 0x7f61b1e6, v182
	v_log_f32_e32 v182, v182
	s_nop 0
	v_floor_f32_e32 v182, v182
	v_max_f32_e32 v182, 0, v182
	v_exp_f32_e64 v183, -v182
	v_add_f32_e32 v80, v80, v182
	v_mul_f32_e32 v81, v81, v183
	v_mul_f32_e32 v180, v180, v183
	v_xor_b32_e32 v64, 0x80000000, v80
	v_mov_b32_e32 v65, v64
	v_mov_b32_e32 v66, v64
	v_mov_b32_e32 v67, v64
	v_mov_b32_e32 v68, v64
	v_mov_b32_e32 v69, v64
	v_mov_b32_e32 v70, v64
	v_mov_b32_e32 v71, v64
	v_mov_b32_e32 v72, v64
	v_mov_b32_e32 v73, v64
	v_mov_b32_e32 v74, v64
	v_mov_b32_e32 v75, v64
	v_mov_b32_e32 v76, v64
	v_mov_b32_e32 v77, v64
	v_mov_b32_e32 v78, v64
	v_mov_b32_e32 v79, v64
	v_sub_f32_e32 v82, v82, v182
	v_sub_f32_e32 v83, v83, v182
	v_sub_f32_e32 v84, v84, v182
	v_sub_f32_e32 v85, v85, v182
	v_sub_f32_e32 v86, v86, v182
	v_sub_f32_e32 v87, v87, v182
	v_sub_f32_e32 v88, v88, v182
	v_sub_f32_e32 v89, v89, v182
	v_sub_f32_e32 v90, v90, v182
	v_sub_f32_e32 v91, v91, v182
	v_sub_f32_e32 v92, v92, v182
	v_sub_f32_e32 v93, v93, v182
	v_sub_f32_e32 v94, v94, v182
	v_sub_f32_e32 v95, v95, v182
	v_sub_f32_e32 v96, v96, v182
	v_sub_f32_e32 v97, v97, v182
	v_sub_f32_e32 v98, v98, v182
	v_sub_f32_e32 v99, v99, v182
	v_sub_f32_e32 v100, v100, v182
	v_sub_f32_e32 v101, v101, v182
	v_sub_f32_e32 v102, v102, v182
	v_sub_f32_e32 v103, v103, v182
	v_sub_f32_e32 v104, v104, v182
	v_sub_f32_e32 v105, v105, v182
	v_sub_f32_e32 v106, v106, v182
	v_sub_f32_e32 v107, v107, v182
	v_sub_f32_e32 v108, v108, v182
	v_sub_f32_e32 v109, v109, v182
	v_sub_f32_e32 v110, v110, v182
	v_sub_f32_e32 v111, v111, v182
	v_sub_f32_e32 v112, v112, v182
	v_sub_f32_e32 v113, v113, v182
	v_mul_f32_e32 v0, v0, v183
	v_mul_f32_e32 v1, v1, v183
	v_mul_f32_e32 v2, v2, v183
	v_mul_f32_e32 v3, v3, v183
	v_mul_f32_e32 v4, v4, v183
	v_mul_f32_e32 v5, v5, v183
	v_mul_f32_e32 v6, v6, v183
	v_mul_f32_e32 v7, v7, v183
	v_mul_f32_e32 v8, v8, v183
	v_mul_f32_e32 v9, v9, v183
	v_mul_f32_e32 v10, v10, v183
	v_mul_f32_e32 v11, v11, v183
	v_mul_f32_e32 v12, v12, v183
	v_mul_f32_e32 v13, v13, v183
	v_mul_f32_e32 v14, v14, v183
	v_mul_f32_e32 v15, v15, v183
	v_mul_f32_e32 v16, v16, v183
	v_mul_f32_e32 v17, v17, v183
	v_mul_f32_e32 v18, v18, v183
	v_mul_f32_e32 v19, v19, v183
	v_mul_f32_e32 v20, v20, v183
	v_mul_f32_e32 v21, v21, v183
	v_mul_f32_e32 v22, v22, v183
	v_mul_f32_e32 v23, v23, v183
	v_mul_f32_e32 v24, v24, v183
	v_mul_f32_e32 v25, v25, v183
	v_mul_f32_e32 v26, v26, v183
	v_mul_f32_e32 v27, v27, v183
	v_mul_f32_e32 v28, v28, v183
	v_mul_f32_e32 v29, v29, v183
	v_mul_f32_e32 v30, v30, v183
	v_mul_f32_e32 v31, v31, v183
	v_mul_f32_e32 v32, v32, v183
	v_mul_f32_e32 v33, v33, v183
	v_mul_f32_e32 v34, v34, v183
	v_mul_f32_e32 v35, v35, v183
	v_mul_f32_e32 v36, v36, v183
	v_mul_f32_e32 v37, v37, v183
	v_mul_f32_e32 v38, v38, v183
	v_mul_f32_e32 v39, v39, v183
	v_mul_f32_e32 v40, v40, v183
	v_mul_f32_e32 v41, v41, v183
	v_mul_f32_e32 v42, v42, v183
	v_mul_f32_e32 v43, v43, v183
	v_mul_f32_e32 v44, v44, v183
	v_mul_f32_e32 v45, v45, v183
	v_mul_f32_e32 v46, v46, v183
	v_mul_f32_e32 v47, v47, v183
	v_mul_f32_e32 v48, v48, v183
	v_mul_f32_e32 v49, v49, v183
	v_mul_f32_e32 v50, v50, v183
	v_mul_f32_e32 v51, v51, v183
	v_mul_f32_e32 v52, v52, v183
	v_mul_f32_e32 v53, v53, v183
	v_mul_f32_e32 v54, v54, v183
	v_mul_f32_e32 v55, v55, v183
	v_mul_f32_e32 v56, v56, v183
	v_mul_f32_e32 v57, v57, v183
	v_mul_f32_e32 v58, v58, v183
	v_mul_f32_e32 v59, v59, v183
	v_mul_f32_e32 v60, v60, v183
	v_mul_f32_e32 v61, v61, v183
	v_mul_f32_e32 v62, v62, v183
	v_mul_f32_e32 v63, v63, v183
	v_lshlrev_b32_e32 v181, 16, v114
	v_and_b32_e32 v114, 0xffff0000, v114
	v_mul_f32_e32 v181, v181, v183
	v_mul_f32_e32 v114, v114, v183
	v_cvt_pk_bf16_f32 v114, v181, v114
	v_lshlrev_b32_e32 v181, 16, v115
	v_and_b32_e32 v115, 0xffff0000, v115
	v_mul_f32_e32 v181, v181, v183
	v_mul_f32_e32 v115, v115, v183
	v_cvt_pk_bf16_f32 v115, v181, v115
	v_lshlrev_b32_e32 v181, 16, v116
	v_and_b32_e32 v116, 0xffff0000, v116
	v_mul_f32_e32 v181, v181, v183
	v_mul_f32_e32 v116, v116, v183
	v_cvt_pk_bf16_f32 v116, v181, v116
	v_lshlrev_b32_e32 v181, 16, v117
	v_and_b32_e32 v117, 0xffff0000, v117
	v_mul_f32_e32 v181, v181, v183
	v_mul_f32_e32 v117, v117, v183
	v_cvt_pk_bf16_f32 v117, v181, v117
	v_lshlrev_b32_e32 v181, 16, v118
	v_and_b32_e32 v118, 0xffff0000, v118
	v_mul_f32_e32 v181, v181, v183
	v_mul_f32_e32 v118, v118, v183
	v_cvt_pk_bf16_f32 v118, v181, v118
	v_lshlrev_b32_e32 v181, 16, v119
	v_and_b32_e32 v119, 0xffff0000, v119
	v_mul_f32_e32 v181, v181, v183
	v_mul_f32_e32 v119, v119, v183
	v_cvt_pk_bf16_f32 v119, v181, v119
	v_lshlrev_b32_e32 v181, 16, v120
	v_and_b32_e32 v120, 0xffff0000, v120
	v_mul_f32_e32 v181, v181, v183
	v_mul_f32_e32 v120, v120, v183
	v_cvt_pk_bf16_f32 v120, v181, v120
	v_lshlrev_b32_e32 v181, 16, v121
	v_and_b32_e32 v121, 0xffff0000, v121
	v_mul_f32_e32 v181, v181, v183
	v_mul_f32_e32 v121, v121, v183
	v_cvt_pk_bf16_f32 v121, v181, v121
	v_lshlrev_b32_e32 v181, 16, v122
	v_and_b32_e32 v122, 0xffff0000, v122
	v_mul_f32_e32 v181, v181, v183
	v_mul_f32_e32 v122, v122, v183
	v_cvt_pk_bf16_f32 v122, v181, v122
	v_lshlrev_b32_e32 v181, 16, v123
	v_and_b32_e32 v123, 0xffff0000, v123
	v_mul_f32_e32 v181, v181, v183
	v_mul_f32_e32 v123, v123, v183
	v_cvt_pk_bf16_f32 v123, v181, v123
	v_lshlrev_b32_e32 v181, 16, v124
	v_and_b32_e32 v124, 0xffff0000, v124
	v_mul_f32_e32 v181, v181, v183
	v_mul_f32_e32 v124, v124, v183
	v_cvt_pk_bf16_f32 v124, v181, v124
	v_lshlrev_b32_e32 v181, 16, v125
	v_and_b32_e32 v125, 0xffff0000, v125
	v_mul_f32_e32 v181, v181, v183
	v_mul_f32_e32 v125, v125, v183
	v_cvt_pk_bf16_f32 v125, v181, v125
	v_lshlrev_b32_e32 v181, 16, v126
	v_and_b32_e32 v126, 0xffff0000, v126
	v_mul_f32_e32 v181, v181, v183
	v_mul_f32_e32 v126, v126, v183
	v_cvt_pk_bf16_f32 v126, v181, v126
	v_lshlrev_b32_e32 v181, 16, v127
	v_and_b32_e32 v127, 0xffff0000, v127
	v_mul_f32_e32 v181, v181, v183
	v_mul_f32_e32 v127, v127, v183
	v_cvt_pk_bf16_f32 v127, v181, v127
	v_lshlrev_b32_e32 v181, 16, v128
	v_and_b32_e32 v128, 0xffff0000, v128
	v_mul_f32_e32 v181, v181, v183
	v_mul_f32_e32 v128, v128, v183
	v_cvt_pk_bf16_f32 v128, v181, v128
	v_lshlrev_b32_e32 v181, 16, v129
	v_and_b32_e32 v129, 0xffff0000, v129
	v_mul_f32_e32 v181, v181, v183
	v_mul_f32_e32 v129, v129, v183
	v_cvt_pk_bf16_f32 v129, v181, v129
.Lat_norescale_8:
	v_add_f32_e32 v81, v81, v180
	s_waitcnt vmcnt(3) lgkmcnt(15)
	s_branch .Lat_bottom_4
.Lat_xlast_7:
	s_waitcnt lgkmcnt(14)
	v_mfma_f32_32x32x16_bf16 v[0:15], v[224:227], v[114:117], v[0:15]
	v_exp_f32_e32 v82, v82
	v_exp_f32_e32 v83, v83
	v_mov_b32_e32 v180, 0
	ds_read_b64_tr_b16 v[224:225], v215 offset:8192
	ds_read_b64_tr_b16 v[226:227], v215 offset:10240
	s_waitcnt lgkmcnt(14)
	v_mfma_f32_32x32x16_bf16 v[16:31], v[228:231], v[114:117], v[16:31]
	v_exp_f32_e32 v84, v84
	v_exp_f32_e32 v85, v85
	v_add_f32_e32 v180, v180, v82
	v_add_f32_e32 v180, v180, v83
	ds_read_b64_tr_b16 v[228:229], v165 offset:8192
	ds_read_b64_tr_b16 v[230:231], v165 offset:10240
	s_waitcnt lgkmcnt(14)
	v_mfma_f32_32x32x16_bf16 v[32:47], v[232:235], v[114:117], v[32:47]
	v_exp_f32_e32 v86, v86
	v_exp_f32_e32 v87, v87
	v_add_f32_e32 v180, v180, v84
	v_add_f32_e32 v180, v180, v85
	ds_read_b64_tr_b16 v[232:233], v216 offset:8192
	ds_read_b64_tr_b16 v[234:235], v216 offset:10240
	s_waitcnt lgkmcnt(14)
	v_mfma_f32_32x32x16_bf16 v[48:63], v[236:239], v[114:117], v[48:63]
	v_exp_f32_e32 v88, v88
	v_exp_f32_e32 v89, v89
	v_add_f32_e32 v180, v180, v86
	v_add_f32_e32 v180, v180, v87
	ds_read_b64_tr_b16 v[236:237], v217 offset:8192
	ds_read_b64_tr_b16 v[238:239], v217 offset:10240
	s_waitcnt lgkmcnt(14)
	v_mfma_f32_32x32x16_bf16 v[0:15], v[240:243], v[118:121], v[0:15]
	v_exp_f32_e32 v90, v90
	v_exp_f32_e32 v91, v91
	v_add_f32_e32 v180, v180, v88
	v_add_f32_e32 v180, v180, v89
	v_cvt_pk_bf16_f32 v114, v82, v83
	ds_read_b64_tr_b16 v[240:241], v215 offset:12288
	ds_read_b64_tr_b16 v[242:243], v215 offset:14336
	s_waitcnt lgkmcnt(14)
	v_mfma_f32_32x32x16_bf16 v[16:31], v[130:133], v[118:121], v[16:31]
	v_exp_f32_e32 v92, v92
	v_exp_f32_e32 v93, v93
	v_add_f32_e32 v180, v180, v90
	v_add_f32_e32 v180, v180, v91
	v_cvt_pk_bf16_f32 v115, v84, v85
	ds_read_b64_tr_b16 v[130:131], v165 offset:12288
	ds_read_b64_tr_b16 v[132:133], v165 offset:14336
	s_waitcnt lgkmcnt(14)
	v_mfma_f32_32x32x16_bf16 v[32:47], v[134:137], v[118:121], v[32:47]
	v_exp_f32_e32 v94, v94
	v_exp_f32_e32 v95, v95
	v_add_f32_e32 v180, v180, v92
	v_add_f32_e32 v180, v180, v93
	v_cvt_pk_bf16_f32 v116, v86, v87
	ds_read_b64_tr_b16 v[134:135], v216 offset:12288
	ds_read_b64_tr_b16 v[136:137], v216 offset:14336
	s_waitcnt lgkmcnt(14)
	v_mfma_f32_32x32x16_bf16 v[48:63], v[184:187], v[118:121], v[48:63]
	v_exp_f32_e32 v96, v96
	v_exp_f32_e32 v97, v97
	v_add_f32_e32 v180, v180, v94
	v_add_f32_e32 v180, v180, v95
	v_cvt_pk_bf16_f32 v117, v88, v89
	ds_read_b64_tr_b16 v[184:185], v217 offset:12288
	ds_read_b64_tr_b16 v[186:187], v217 offset:14336
	s_waitcnt lgkmcnt(14)
	v_mfma_f32_32x32x16_bf16 v[0:15], v[224:227], v[122:125], v[0:15]
	v_exp_f32_e32 v98, v98
	v_exp_f32_e32 v99, v99
	v_add_f32_e32 v180, v180, v96
	v_add_f32_e32 v180, v180, v97
	v_cvt_pk_bf16_f32 v118, v90, v91
	s_waitcnt lgkmcnt(12)
	v_mfma_f32_32x32x16_bf16 v[16:31], v[228:231], v[122:125], v[16:31]
	v_exp_f32_e32 v100, v100
	v_exp_f32_e32 v101, v101
	v_add_f32_e32 v180, v180, v98
	v_add_f32_e32 v180, v180, v99
	v_cvt_pk_bf16_f32 v119, v92, v93
	s_waitcnt lgkmcnt(10)
	v_mfma_f32_32x32x16_bf16 v[32:47], v[232:235], v[122:125], v[32:47]
	v_exp_f32_e32 v102, v102
	v_exp_f32_e32 v103, v103
	v_add_f32_e32 v180, v180, v100
	v_add_f32_e32 v180, v180, v101
	v_cvt_pk_bf16_f32 v120, v94, v95
	s_waitcnt lgkmcnt(8)
	v_mfma_f32_32x32x16_bf16 v[48:63], v[236:239], v[122:125], v[48:63]
	v_exp_f32_e32 v104, v104
	v_exp_f32_e32 v105, v105
	v_add_f32_e32 v180, v180, v102
	v_add_f32_e32 v180, v180, v103
	v_cvt_pk_bf16_f32 v121, v96, v97
	ds_read_b128 v[224:227], v188
	ds_read_b128 v[228:231], v189
	ds_read_b128 v[232:235], v222
	ds_read_b128 v[236:239], v223
	s_waitcnt lgkmcnt(10)
	v_mfma_f32_32x32x16_bf16 v[0:15], v[240:243], v[126:129], v[0:15]
	v_exp_f32_e32 v106, v106
	v_exp_f32_e32 v107, v107
	v_add_f32_e32 v180, v180, v104
	v_add_f32_e32 v180, v180, v105
	v_cvt_pk_bf16_f32 v122, v98, v99
	s_waitcnt lgkmcnt(8)
	v_mfma_f32_32x32x16_bf16 v[16:31], v[130:133], v[126:129], v[16:31]
	v_exp_f32_e32 v108, v108
	v_exp_f32_e32 v109, v109
	v_add_f32_e32 v180, v180, v106
	v_add_f32_e32 v180, v180, v107
	v_cvt_pk_bf16_f32 v123, v100, v101
	s_waitcnt lgkmcnt(6)
	v_mfma_f32_32x32x16_bf16 v[32:47], v[134:137], v[126:129], v[32:47]
	v_exp_f32_e32 v110, v110
	v_exp_f32_e32 v111, v111
	v_add_f32_e32 v180, v180, v108
	v_add_f32_e32 v180, v180, v109
	v_cvt_pk_bf16_f32 v124, v102, v103
	s_waitcnt lgkmcnt(4)
	v_mfma_f32_32x32x16_bf16 v[48:63], v[184:187], v[126:129], v[48:63]
	v_exp_f32_e32 v112, v112
	v_exp_f32_e32 v113, v113
	v_add_f32_e32 v180, v180, v110
	v_add_f32_e32 v180, v180, v111
	v_cvt_pk_bf16_f32 v125, v104, v105
	s_nop 0
	v_add_f32_e32 v180, v180, v112
	v_add_f32_e32 v180, v180, v113
	v_cvt_pk_bf16_f32 v126, v106, v107
	v_cvt_pk_bf16_f32 v127, v108, v109
	v_cvt_pk_bf16_f32 v128, v110, v111
	v_cvt_pk_bf16_f32 v129, v112, v113
	v_cmp_ngt_f32_e32 vcc, s23, v180
	s_cbranch_vccz .Lat_norescale_9
	ds_bpermute_b32 v182, v214, v180
	s_waitcnt lgkmcnt(0)
	v_add_f32_e32 v182, v180, v182
	v_min_f32_e32 v182, 0x7f61b1e6, v182
	v_log_f32_e32 v182, v182
	s_nop 0
	v_floor_f32_e32 v182, v182
	v_max_f32_e32 v182, 0, v182
	v_exp_f32_e64 v183, -v182
	v_add_f32_e32 v80, v80, v182
	v_mul_f32_e32 v81, v81, v183
	v_mul_f32_e32 v180, v180, v183
	v_xor_b32_e32 v64, 0x80000000, v80
	v_mov_b32_e32 v65, v64
	v_mov_b32_e32 v66, v64
	v_mov_b32_e32 v67, v64
	v_mov_b32_e32 v68, v64
	v_mov_b32_e32 v69, v64
	v_mov_b32_e32 v70, v64
	v_mov_b32_e32 v71, v64
	v_mov_b32_e32 v72, v64
	v_mov_b32_e32 v73, v64
	v_mov_b32_e32 v74, v64
	v_mov_b32_e32 v75, v64
	v_mov_b32_e32 v76, v64
	v_mov_b32_e32 v77, v64
	v_mov_b32_e32 v78, v64
	v_mov_b32_e32 v79, v64
	v_mul_f32_e32 v82, v82, v183
	v_mul_f32_e32 v83, v83, v183
	v_mul_f32_e32 v84, v84, v183
	v_mul_f32_e32 v85, v85, v183
	v_mul_f32_e32 v86, v86, v183
	v_mul_f32_e32 v87, v87, v183
	v_mul_f32_e32 v88, v88, v183
	v_mul_f32_e32 v89, v89, v183
	v_mul_f32_e32 v90, v90, v183
	v_mul_f32_e32 v91, v91, v183
	v_mul_f32_e32 v92, v92, v183
	v_mul_f32_e32 v93, v93, v183
	v_mul_f32_e32 v94, v94, v183
	v_mul_f32_e32 v95, v95, v183
	v_mul_f32_e32 v96, v96, v183
	v_mul_f32_e32 v97, v97, v183
	v_mul_f32_e32 v98, v98, v183
	v_mul_f32_e32 v99, v99, v183
	v_mul_f32_e32 v100, v100, v183
	v_mul_f32_e32 v101, v101, v183
	v_mul_f32_e32 v102, v102, v183
	v_mul_f32_e32 v103, v103, v183
	v_mul_f32_e32 v104, v104, v183
	v_mul_f32_e32 v105, v105, v183
	v_mul_f32_e32 v106, v106, v183
	v_mul_f32_e32 v107, v107, v183
	v_mul_f32_e32 v108, v108, v183
	v_mul_f32_e32 v109, v109, v183
	v_mul_f32_e32 v110, v110, v183
	v_mul_f32_e32 v111, v111, v183
	v_mul_f32_e32 v112, v112, v183
	v_mul_f32_e32 v113, v113, v183
	v_mul_f32_e32 v0, v0, v183
	v_mul_f32_e32 v1, v1, v183
	v_mul_f32_e32 v2, v2, v183
	v_mul_f32_e32 v3, v3, v183
	v_mul_f32_e32 v4, v4, v183
	v_mul_f32_e32 v5, v5, v183
	v_mul_f32_e32 v6, v6, v183
	v_mul_f32_e32 v7, v7, v183
	v_mul_f32_e32 v8, v8, v183
	v_mul_f32_e32 v9, v9, v183
	v_mul_f32_e32 v10, v10, v183
	v_mul_f32_e32 v11, v11, v183
	v_mul_f32_e32 v12, v12, v183
	v_mul_f32_e32 v13, v13, v183
	v_mul_f32_e32 v14, v14, v183
	v_mul_f32_e32 v15, v15, v183
	v_mul_f32_e32 v16, v16, v183
	v_mul_f32_e32 v17, v17, v183
	v_mul_f32_e32 v18, v18, v183
	v_mul_f32_e32 v19, v19, v183
	v_mul_f32_e32 v20, v20, v183
	v_mul_f32_e32 v21, v21, v183
	v_mul_f32_e32 v22, v22, v183
	v_mul_f32_e32 v23, v23, v183
	v_mul_f32_e32 v24, v24, v183
	v_mul_f32_e32 v25, v25, v183
	v_mul_f32_e32 v26, v26, v183
	v_mul_f32_e32 v27, v27, v183
	v_mul_f32_e32 v28, v28, v183
	v_mul_f32_e32 v29, v29, v183
	v_mul_f32_e32 v30, v30, v183
	v_mul_f32_e32 v31, v31, v183
	v_mul_f32_e32 v32, v32, v183
	v_mul_f32_e32 v33, v33, v183
	v_mul_f32_e32 v34, v34, v183
	v_mul_f32_e32 v35, v35, v183
	v_mul_f32_e32 v36, v36, v183
	v_mul_f32_e32 v37, v37, v183
	v_mul_f32_e32 v38, v38, v183
	v_mul_f32_e32 v39, v39, v183
	v_mul_f32_e32 v40, v40, v183
	v_mul_f32_e32 v41, v41, v183
	v_mul_f32_e32 v42, v42, v183
	v_mul_f32_e32 v43, v43, v183
	v_mul_f32_e32 v44, v44, v183
	v_mul_f32_e32 v45, v45, v183
	v_mul_f32_e32 v46, v46, v183
	v_mul_f32_e32 v47, v47, v183
	v_mul_f32_e32 v48, v48, v183
	v_mul_f32_e32 v49, v49, v183
	v_mul_f32_e32 v50, v50, v183
	v_mul_f32_e32 v51, v51, v183
	v_mul_f32_e32 v52, v52, v183
	v_mul_f32_e32 v53, v53, v183
	v_mul_f32_e32 v54, v54, v183
	v_mul_f32_e32 v55, v55, v183
	v_mul_f32_e32 v56, v56, v183
	v_mul_f32_e32 v57, v57, v183
	v_mul_f32_e32 v58, v58, v183
	v_mul_f32_e32 v59, v59, v183
	v_mul_f32_e32 v60, v60, v183
	v_mul_f32_e32 v61, v61, v183
	v_mul_f32_e32 v62, v62, v183
	v_mul_f32_e32 v63, v63, v183
	v_cvt_pk_bf16_f32 v114, v82, v83
	v_cvt_pk_bf16_f32 v115, v84, v85
	v_cvt_pk_bf16_f32 v116, v86, v87
	v_cvt_pk_bf16_f32 v117, v88, v89
	v_cvt_pk_bf16_f32 v118, v90, v91
	v_cvt_pk_bf16_f32 v119, v92, v93
	v_cvt_pk_bf16_f32 v120, v94, v95
	v_cvt_pk_bf16_f32 v121, v96, v97
	v_cvt_pk_bf16_f32 v122, v98, v99
	v_cvt_pk_bf16_f32 v123, v100, v101
	v_cvt_pk_bf16_f32 v124, v102, v103
	v_cvt_pk_bf16_f32 v125, v104, v105
	v_cvt_pk_bf16_f32 v126, v106, v107
	v_cvt_pk_bf16_f32 v127, v108, v109
	v_cvt_pk_bf16_f32 v128, v110, v111
	v_cvt_pk_bf16_f32 v129, v112, v113

.Lat_pvonly_6:
	s_waitcnt lgkmcnt(14)
	v_mfma_f32_32x32x16_bf16 v[0:15], v[224:227], v[114:117], v[0:15]
	ds_read_b64_tr_b16 v[224:225], v215 offset:8192
	ds_read_b64_tr_b16 v[226:227], v215 offset:10240
	s_waitcnt lgkmcnt(14)
	v_mfma_f32_32x32x16_bf16 v[16:31], v[228:231], v[114:117], v[16:31]
	ds_read_b64_tr_b16 v[228:229], v165 offset:8192
	ds_read_b64_tr_b16 v[230:231], v165 offset:10240
	s_waitcnt lgkmcnt(14)
	v_mfma_f32_32x32x16_bf16 v[32:47], v[232:235], v[114:117], v[32:47]
	ds_read_b64_tr_b16 v[232:233], v216 offset:8192
	ds_read_b64_tr_b16 v[234:235], v216 offset:10240
	s_waitcnt lgkmcnt(14)
	v_mfma_f32_32x32x16_bf16 v[48:63], v[236:239], v[114:117], v[48:63]
	ds_read_b64_tr_b16 v[236:237], v217 offset:8192
	ds_read_b64_tr_b16 v[238:239], v217 offset:10240
	s_waitcnt lgkmcnt(14)
	v_mfma_f32_32x32x16_bf16 v[0:15], v[240:243], v[118:121], v[0:15]
	ds_read_b64_tr_b16 v[240:241], v215 offset:12288
	ds_read_b64_tr_b16 v[242:243], v215 offset:14336
	s_waitcnt lgkmcnt(14)
	v_mfma_f32_32x32x16_bf16 v[16:31], v[130:133], v[118:121], v[16:31]
	ds_read_b64_tr_b16 v[130:131], v165 offset:12288
	ds_read_b64_tr_b16 v[132:133], v165 offset:14336
	s_waitcnt lgkmcnt(14)
	v_mfma_f32_32x32x16_bf16 v[32:47], v[134:137], v[118:121], v[32:47]
	ds_read_b64_tr_b16 v[134:135], v216 offset:12288
	ds_read_b64_tr_b16 v[136:137], v216 offset:14336
	s_waitcnt lgkmcnt(14)
	v_mfma_f32_32x32x16_bf16 v[48:63], v[184:187], v[118:121], v[48:63]
	ds_read_b64_tr_b16 v[184:185], v217 offset:12288
	ds_read_b64_tr_b16 v[186:187], v217 offset:14336
	s_waitcnt lgkmcnt(14)
	v_mfma_f32_32x32x16_bf16 v[0:15], v[224:227], v[122:125], v[0:15]
	s_waitcnt lgkmcnt(12)
	v_mfma_f32_32x32x16_bf16 v[16:31], v[228:231], v[122:125], v[16:31]
	s_waitcnt lgkmcnt(10)
	v_mfma_f32_32x32x16_bf16 v[32:47], v[232:235], v[122:125], v[32:47]
	s_waitcnt lgkmcnt(8)
	v_mfma_f32_32x32x16_bf16 v[48:63], v[236:239], v[122:125], v[48:63]
	s_waitcnt lgkmcnt(6)
	v_mfma_f32_32x32x16_bf16 v[0:15], v[240:243], v[126:129], v[0:15]
	s_waitcnt lgkmcnt(4)
	v_mfma_f32_32x32x16_bf16 v[16:31], v[130:133], v[126:129], v[16:31]
	s_waitcnt lgkmcnt(2)
	v_mfma_f32_32x32x16_bf16 v[32:47], v[134:137], v[126:129], v[32:47]
	s_waitcnt lgkmcnt(0)
	v_mfma_f32_32x32x16_bf16 v[48:63], v[184:187], v[126:129], v[48:63]
.Lat_noqk_3:
	s_add_i32 m0, s13, s68
	s_nop 0
	global_load_lds_dwordx4 v154, s[14:15]
	s_add_i32 m0, s17, s69
	s_nop 0
	global_load_lds_dwordx4 v155, s[18:19]
	s_add_i32 m0, m0, 0x400
	s_nop 0
	global_load_lds_dwordx4 v156, s[18:19]
	s_add_i32 s13, s13, 8192
	s_cmp_eq_u32 s13, 32768
	s_cselect_b32 s13, 0, s13
	s_add_i32 s17, s17, 16384
	s_cmp_eq_u32 s17, 114688
	s_cselect_b32 s17, 32768, s17
	s_add_i32 s85, s85, 1
	s_cmp_lt_u32 s85, s6
	s_cselect_b32 s8, 0x40000, 0
	s_add_u32 s14, s14, s8
	s_addc_u32 s15, s15, 0
	s_add_u32 s18, s18, s8
	s_addc_u32 s19, s19, 0
	s_add_i32 s5, s5, 1
	s_add_i32 s12, s12, 8192
	s_cmp_eq_u32 s12, 32768
	s_cselect_b32 s12, 0, s12
	s_add_i32 s84, s84, 16384
	s_cmp_eq_u32 s84, 114688
	s_cselect_b32 s84, 32768, s84
	s_add_i32 s16, s81, 1
	s_cmp_gt_i32 s5, s16
	s_cbranch_scc1 .Lat_novpre_5
	v_add_u32_e32 v215, s84, v161
	v_add_u32_e32 v165, s84, v162
	v_add_u32_e32 v216, s84, v163
	v_add_u32_e32 v217, s84, v164
	ds_read_b64_tr_b16 v[224:225], v215 offset:0
	ds_read_b64_tr_b16 v[226:227], v215 offset:2048
	ds_read_b64_tr_b16 v[228:229], v165 offset:0
	ds_read_b64_tr_b16 v[230:231], v165 offset:2048
	ds_read_b64_tr_b16 v[232:233], v216 offset:0
	ds_read_b64_tr_b16 v[234:235], v216 offset:2048
	ds_read_b64_tr_b16 v[236:237], v217 offset:0
	ds_read_b64_tr_b16 v[238:239], v217 offset:2048
	ds_read_b64_tr_b16 v[240:241], v215 offset:4096
	ds_read_b64_tr_b16 v[242:243], v215 offset:6144
	ds_read_b64_tr_b16 v[130:131], v165 offset:4096
	ds_read_b64_tr_b16 v[132:133], v165 offset:6144
	ds_read_b64_tr_b16 v[134:135], v216 offset:4096
	ds_read_b64_tr_b16 v[136:137], v216 offset:6144
	ds_read_b64_tr_b16 v[184:185], v217 offset:4096
	ds_read_b64_tr_b16 v[186:187], v217 offset:6144
	s_waitcnt vmcnt(3) lgkmcnt(15)
	s_branch .Lat_bottom_4
